# combo13 + NSA part-B loops: second sub-tile's K-fragment ds_reads issued at the top of the tile step (hidden behind the first sub-tile)
# speedup vs baseline: 1.0021x; 1.0021x over previous
.LBB0_709:
	v_lshrrev_b32_e32 v32, s33, v59
	v_and_b32_e32 v32, 1, v32
	s_lshl_b32 s6, s33, 6
	v_add_u32_e32 v79, s44, v120
	v_cmp_eq_u32_e64 s[44:45], 1, v32
	v_add_u32_e32 v77, v79, v141
	v_add_u32_e32 v198, v79, v123
	s_cmp_gt_i32 s6, s17
	v_cndmask_b32_e64 v96, 0, 1, s[44:45]
	ds_read_b128 v[218:221], v198 offset:4608
	ds_read_b128 v[222:225], v198 offset:4640
	ds_read_b128 v[226:229], v198 offset:4672
	ds_read_b128 v[230:233], v198 offset:4704
	s_cbranch_scc1 .LBB0_714
	v_cmp_ne_u32_e32 vcc, 0, v96
	s_cbranch_vccz .LBB0_714
	v_add_u32_e32 v36, v79, v123
	ds_read_b128 v[32:35], v36
	ds_read_b128 v[98:101], v36 offset:32
	ds_read_b128 v[146:149], v36 offset:64
	ds_read_b128 v[150:153], v36 offset:96
	s_setprio 1
	s_waitcnt lgkmcnt(0)
	v_mfma_f32_32x32x16_bf16 v[32:47], v[32:35], v[80:83], 0
	v_mfma_f32_32x32x16_bf16 v[32:47], v[98:101], v[84:87], v[32:47]
	v_mfma_f32_32x32x16_bf16 v[32:47], v[146:149], v[88:91], v[32:47]
	v_mfma_f32_32x32x16_bf16 v[32:47], v[150:153], v[92:95], v[32:47]
	s_setprio 0
	s_sub_i32 m0, s17, 62
	s_cmp_le_i32 s6, m0
	s_cbranch_scc0 .Lsel0_masked
	v_cndmask_b32_e64 v166, v212, 0, s[44:45]
	s_nop 7
	v_fma_f32 v119, v32, s28, v166
	v_fma_f32 v118, v33, s28, v166
	v_fma_f32 v103, v34, s28, v166
	v_fma_f32 v102, v35, s28, v166
	v_fma_f32 v101, v36, s28, v166
	v_fma_f32 v100, v37, s28, v166
	v_fma_f32 v99, v38, s28, v166
	v_fma_f32 v98, v39, s28, v166
	v_fma_f32 v97, v40, s28, v166
	v_fma_f32 v40, v41, s28, v166
	v_fma_f32 v39, v42, s28, v166
	v_fma_f32 v38, v43, s28, v166
	v_fma_f32 v37, v44, s28, v166
	v_fma_f32 v36, v45, s28, v166
	v_fma_f32 v35, v46, s28, v166
	v_fma_f32 v34, v47, s28, v166
	v_max_f32_e32 v43, v35, v34
	v_max_f32_e32 v32, v103, v102
	v_max_f32_e32 v33, v99, v98
	v_max_f32_e32 v41, v97, v40
	v_max_f32_e32 v42, v39, v38
	v_max3_f32 v43, v37, v36, v43
	v_max3_f32 v32, v119, v118, v32
	v_max3_f32 v33, v101, v100, v33
	v_max3_f32 v41, v41, v42, v43
	v_max3_f32 v32, v32, v33, v41
	s_branch .Lsel0_join

.LBB0_714:
	s_or_b32 s6, s6, 32
	s_cmp_gt_i32 s6, s17
	s_cbranch_scc1 .LBB0_719
	v_cmp_ne_u32_e32 vcc, 0, v96
	s_cbranch_vccz .LBB0_719
	v_add_u32_e32 v36, v79, v123
	s_setprio 1
	s_waitcnt lgkmcnt(0)
	v_mfma_f32_32x32x16_bf16 v[32:47], v[218:221], v[80:83], 0
	v_mfma_f32_32x32x16_bf16 v[32:47], v[222:225], v[84:87], v[32:47]
	v_mfma_f32_32x32x16_bf16 v[32:47], v[226:229], v[88:91], v[32:47]
	v_mfma_f32_32x32x16_bf16 v[32:47], v[230:233], v[92:95], v[32:47]
	s_setprio 0
	s_sub_i32 m0, s17, 62
	s_cmp_le_i32 s6, m0
	s_cbranch_scc0 .Lsel1_masked
	v_cndmask_b32_e64 v166, v212, 0, s[44:45]
	s_nop 7
	v_fma_f32 v103, v32, s28, v166
	v_fma_f32 v102, v33, s28, v166
	v_fma_f32 v101, v34, s28, v166
	v_fma_f32 v100, v35, s28, v166
	v_fma_f32 v99, v36, s28, v166
	v_fma_f32 v98, v37, s28, v166
	v_fma_f32 v97, v38, s28, v166
	v_fma_f32 v96, v39, s28, v166
	v_fma_f32 v79, v40, s28, v166
	v_fma_f32 v40, v41, s28, v166
	v_fma_f32 v39, v42, s28, v166
	v_fma_f32 v38, v43, s28, v166
	v_fma_f32 v37, v44, s28, v166
	v_fma_f32 v36, v45, s28, v166
	v_fma_f32 v35, v46, s28, v166
	v_fma_f32 v34, v47, s28, v166
	v_max_f32_e32 v43, v35, v34
	v_max_f32_e32 v32, v101, v100
	v_max_f32_e32 v33, v97, v96
	v_max_f32_e32 v41, v79, v40
	v_max_f32_e32 v42, v39, v38
	v_max3_f32 v43, v37, v36, v43
	v_max3_f32 v32, v103, v102, v32
	v_max3_f32 v33, v99, v98, v33
	v_max3_f32 v41, v41, v42, v43
	v_max3_f32 v32, v32, v33, v41
	s_branch .Lsel1_join

.LBB0_728:
	s_cmp_le_i32 s6, s17
	v_add_u32_e32 v64, s18, v120
	s_cselect_b64 s[20:21], -1, 0
	s_add_i32 s18, s6, 31
	s_cmp_ge_i32 s18, s19
	s_cselect_b64 s[38:39], -1, 0
	s_and_b64 s[20:21], s[20:21], s[38:39]
	v_add_u32_e32 v150, v64, v141
	s_andn2_b64 vcc, exec, s[20:21]
	v_add_u32_e32 v152, v64, v123
	s_nop 0
	ds_read_b128 v[218:221], v152 offset:4608
	ds_read_b128 v[222:225], v152 offset:4640
	ds_read_b128 v[226:229], v152 offset:4672
	ds_read_b128 v[230:233], v152 offset:4704
	s_cbranch_vccnz .LBB0_732
	ds_read_b128 v[64:67], v152
	ds_read_b128 v[154:157], v152 offset:32
	ds_read_b128 v[158:161], v152 offset:64
	ds_read_b128 v[162:165], v152 offset:96
	s_setprio 1
	s_waitcnt lgkmcnt(0)
	v_mfma_f32_32x32x16_bf16 v[64:79], v[64:67], v[80:83], 0
	v_mfma_f32_32x32x16_bf16 v[64:79], v[154:157], v[84:87], v[64:79]
	v_mfma_f32_32x32x16_bf16 v[64:79], v[158:161], v[88:91], v[64:79]
	v_mfma_f32_32x32x16_bf16 v[64:79], v[162:165], v[92:95], v[64:79]
	s_setprio 0
	s_nop 10
	s_sub_i32 m0, s17, 62
	s_cmp_le_i32 s6, m0
	s_cbranch_scc0 .Lwin0_masked
	s_add_i32 m0, s19, 31
	s_cmp_ge_i32 s6, m0
	s_cbranch_scc0 .Lwin0_masked
	v_mul_f32_e32 v162, 0x3e38aa3b, v64
	v_mul_f32_e32 v161, 0x3e38aa3b, v65
	v_mul_f32_e32 v160, 0x3e38aa3b, v66
	v_mul_f32_e32 v159, 0x3e38aa3b, v67
	v_mul_f32_e32 v158, 0x3e38aa3b, v68
	v_mul_f32_e32 v157, 0x3e38aa3b, v69
	v_mul_f32_e32 v156, 0x3e38aa3b, v70
	v_mul_f32_e32 v155, 0x3e38aa3b, v71
	v_max_f32_e32 v69, v156, v155
	v_mul_f32_e32 v154, 0x3e38aa3b, v72
	v_max3_f32 v69, v158, v157, v69
	v_mul_f32_e32 v72, 0x3e38aa3b, v73
	v_max_f32_e32 v73, v154, v72
	v_mul_f32_e32 v71, 0x3e38aa3b, v74
	v_mul_f32_e32 v70, 0x3e38aa3b, v75
	v_max_f32_e32 v74, v71, v70
	v_mul_f32_e32 v68, 0x3e38aa3b, v76
	v_mul_f32_e32 v67, 0x3e38aa3b, v77
	v_mul_f32_e32 v66, 0x3e38aa3b, v78
	v_max_f32_e32 v64, v160, v159
	v_max3_f32 v64, v162, v161, v64
	v_mul_f32_e32 v65, 0x3e38aa3b, v79
	v_max_f32_e32 v75, v66, v65
	v_max3_f32 v75, v68, v67, v75
	v_max3_f32 v73, v73, v74, v75
	v_max3_f32 v64, v64, v69, v73
	s_branch .Lwin0_join

.LBB0_733:
	s_add_i32 s18, s6, 32
	s_cmp_le_i32 s18, s17
	s_cselect_b64 s[20:21], -1, 0
	s_add_i32 s18, s6, 63
	s_cmp_ge_i32 s18, s19
	s_cselect_b64 s[38:39], -1, 0
	s_and_b64 s[20:21], s[20:21], s[38:39]
	s_andn2_b64 vcc, exec, s[20:21]
	s_cbranch_vccnz .LBB0_724
	s_setprio 1
	s_waitcnt lgkmcnt(0)
	v_mfma_f32_32x32x16_bf16 v[64:79], v[218:221], v[80:83], 0
	v_mfma_f32_32x32x16_bf16 v[64:79], v[222:225], v[84:87], v[64:79]
	v_mfma_f32_32x32x16_bf16 v[64:79], v[226:229], v[88:91], v[64:79]
	v_mfma_f32_32x32x16_bf16 v[64:79], v[230:233], v[92:95], v[64:79]
	s_setprio 0
	v_subrev_u32_e32 v151, 32, v147
	s_nop 9
	s_sub_i32 m0, s17, 94
	s_cmp_le_i32 s6, m0
	s_cbranch_scc0 .Lwin1_masked
	s_add_i32 m0, s19, -1
	s_cmp_ge_i32 s6, m0
	s_cbranch_scc0 .Lwin1_masked
	v_mul_f32_e32 v161, 0x3e38aa3b, v64
	v_mul_f32_e32 v160, 0x3e38aa3b, v65
	v_mul_f32_e32 v159, 0x3e38aa3b, v66
	v_mul_f32_e32 v158, 0x3e38aa3b, v67
	v_mul_f32_e32 v157, 0x3e38aa3b, v68
	v_mul_f32_e32 v156, 0x3e38aa3b, v69
	v_mul_f32_e32 v155, 0x3e38aa3b, v70
	v_mul_f32_e32 v154, 0x3e38aa3b, v71
	v_max_f32_e32 v69, v155, v154
	v_mul_f32_e32 v152, 0x3e38aa3b, v72
	v_max3_f32 v69, v157, v156, v69
	v_mul_f32_e32 v72, 0x3e38aa3b, v73
	v_max_f32_e32 v73, v152, v72
	v_mul_f32_e32 v71, 0x3e38aa3b, v74
	v_mul_f32_e32 v70, 0x3e38aa3b, v75
	v_max_f32_e32 v74, v71, v70
	v_mul_f32_e32 v68, 0x3e38aa3b, v76
	v_mul_f32_e32 v67, 0x3e38aa3b, v77
	v_mul_f32_e32 v66, 0x3e38aa3b, v78
	v_max_f32_e32 v64, v159, v158
	v_max3_f32 v64, v161, v160, v64
	v_mul_f32_e32 v65, 0x3e38aa3b, v79
	v_max_f32_e32 v75, v66, v65
	v_max3_f32 v75, v68, v67, v75
	v_max3_f32 v73, v73, v74, v75
	v_max3_f32 v64, v64, v69, v73
	s_branch .Lwin1_join
